# speedup vs baseline: 1.0406x; 1.0286x over previous
; __device__ __forceinline__ void p0_transpose_item(const float* W, int K, int N, const float* gain, const float* gain2  , bf16_t* WT, LAS unsigned* scr, int item, int lane) {
;     const int nblk = N / 64, kb = item / nblk, nb = item % nblk, k0 = 64 * kb, n0 = 64 * nb;
;     if (gain2 && k0 >= 1024) gain = gain2 - 1024;
;     const int n4 = lane & 15, kq = lane >> 4;
;     f32x4 r0[8], r1[8];
;     const float* src = W + (size_t)(k0 + 2 * kq) * N + n0 + 4 * n4;
; #pragma unroll
;     for (int j = 0; j < 8; ++j) { r0[j] = __builtin_nontemporal_load((const f32x4*)(src + (size_t)(8 * j) * N)); r1[j] = __builtin_nontemporal_load((const f32x4*)(src + (size_t)(8 * j + 1) * N)); }
; #pragma unroll
;     for (int j = 0; j < 8; ++j) {
;         float g0 = 1.f, g1 = 1.f; if (gain) { g0 = gain[k0 + 8 * j + 2 * kq]; g1 = gain[k0 + 8 * j + 2 * kq + 1]; }
; #pragma unroll
;         for (int i = 0; i < 4; ++i) scr[(4 * n4 + i) * 32 + (((j ^ (n4 & 7)) << 2) | kq)] = pk2(r0[j][i] * g0, r1[j][i] * g1);
;     }
; __device__ __forceinline__ void p0_prologue(const Params& p, LAS unsigned char* lds, int tid) {
;     ...
;     constexpr int I_IN = (DM / 64) * (INW / 64), I_GLU = (1024 / 64) * (1024 / 64), I_OUT = (DM / 64) * (DM / 64), I_UP = (DM / 64) * (DFF / 64), I_DN = (DFF / 64) * (DM / 64);
;     constexpr int I_LAYER = I_IN + I_GLU + I_OUT + I_UP + I_DN;
;     for (int it = gw; it < I_LAYER * DEPTH; it += NGW) {
;         const int l = it / I_LAYER; int r = it % I_LAYER;
;         unsigned char* wl = p.ws + (size_t)l * LAYER_BYTES;
;         if (r < I_IN) { p0_transpose_item(p.in[3] + (size_t)l * DM * INW, DM, INW, p.in[2] + l * DM, nullptr, (bf16_t*)(wl + LO_WIN), scr, r, lane); continue; } r -= I_IN;
;         if (r < I_UP) { p0_transpose_item(p.in[21] + (size_t)l * DM * DFF, DM, DFF, p.in[20] + l * DM, nullptr, (bf16_t*)(wl + LO_WUP), scr, r, lane); continue; } r -= I_UP;
;         if (r < I_DN) { p0_transpose_item(p.in[22] + (size_t)l * DFF * DM, DFF, DM, nullptr, nullptr, (bf16_t*)(wl + LO_WDN), scr, r, lane); continue; } r -= I_DN;
;         if (r < I_GLU) { p0_transpose_item(p.in[15] + (size_t)l * 1024 * 1024, 1024, 1024, nullptr, nullptr, (bf16_t*)(wl + LO_WGLU), scr, r, lane); continue; } r -= I_GLU;
;         p0_transpose_item(p.in[19] + (size_t)l * DM * DM, DM, DM, p.in[17] + l * 1024, p.in[18] + l * 1024, (bf16_t*)(wl + LO_WOUT), scr, r, lane);
;     }
.LBB0_114:
	v_writelane_b32 v253, s2, 34
	s_or_b64 exec, exec, s[12:13]
	s_movk_i32 s0, 0x500
	v_cmp_gt_i32_e32 vcc, s0, v66
	s_and_saveexec_b64 s[4:5], vcc
	s_cbranch_execz .LBB0_181
	v_lshl_add_u32 v3, v11, 13, 0
	v_lshrrev_b32_e32 v4, 4, v10
	v_lshlrev_b32_e32 v7, 4, v201
	v_lshl_add_u32 v6, v4, 2, v3
	v_and_b32_e32 v7, 0x70, v7
	s_movk_i32 s1, 0x50
	v_lshlrev_b32_e32 v5, 2, v10
	s_movk_i32 s0, 0x70
	v_xad_u32 v91, v7, s1, v6
	s_movk_i32 s1, 0x60
	v_lshrrev_b32_e32 v94, 3, v10
	v_add_u32_e32 v71, v6, v7
	v_xad_u32 v87, v7, 16, v6
	v_xad_u32 v88, v7, 32, v6
	v_xad_u32 v89, v7, 48, v6
	v_xad_u32 v90, v7, 64, v6
	v_xad_u32 v92, v7, s1, v6
	v_xad_u32 v93, v7, s0, v6
	v_bitop3_b32 v7, v94, 28, v5 bitop3:0x48
	v_or_b32_e32 v96, 8, v94
	v_lshlrev_b32_e32 v6, 7, v94
	v_lshlrev_b32_e32 v7, 2, v7
	v_bitop3_b32 v8, v96, 28, v5 bitop3:0x48
	v_add3_u32 v95, v3, v6, v7
	v_lshlrev_b32_e32 v6, 7, v96
	v_lshlrev_b32_e32 v8, 2, v8
	v_or_b32_e32 v98, 16, v94
	v_add3_u32 v97, v3, v6, v8
	v_bitop3_b32 v8, v98, 28, v5 bitop3:0x48
	v_lshlrev_b32_e32 v6, 7, v98
	v_lshlrev_b32_e32 v8, 2, v8
	v_or_b32_e32 v100, 24, v94
	v_add3_u32 v99, v3, v6, v8
	v_bitop3_b32 v8, v100, 28, v5 bitop3:0x48
	v_lshlrev_b32_e32 v6, 7, v100
	v_lshlrev_b32_e32 v8, 2, v8
	v_or_b32_e32 v102, 32, v94
	v_add3_u32 v101, v3, v6, v8
	v_lshlrev_b32_e32 v6, 7, v102
	v_or_b32_e32 v104, 40, v94
	v_add3_u32 v103, v3, v6, v7
	v_bitop3_b32 v7, v104, 28, v5 bitop3:0x48
	v_readlane_b32 s36, v253, 18
	v_lshlrev_b32_e32 v6, 7, v104
	v_lshlrev_b32_e32 v7, 2, v7
	v_or_b32_e32 v106, 48, v94
	v_readlane_b32 s40, v253, 22
	v_readlane_b32 s41, v253, 23
	v_add3_u32 v105, v3, v6, v7
	v_bitop3_b32 v7, v106, 28, v5 bitop3:0x48
	v_or_b32_e32 v108, 56, v94
	v_readlane_b32 s37, v253, 19
	v_readlane_b32 s38, v253, 20
	v_readlane_b32 s39, v253, 21
	v_readlane_b32 s42, v253, 24
	v_readlane_b32 s43, v253, 25
	v_readlane_b32 s44, v253, 26
	v_readlane_b32 s45, v253, 27
	v_readlane_b32 s46, v253, 28
	v_readlane_b32 s47, v253, 29
	v_readlane_b32 s48, v253, 30
	v_readlane_b32 s49, v253, 31
	v_readlane_b32 s50, v253, 32
	v_readlane_b32 s51, v253, 33
	s_cmp_lg_u64 s[40:41], 0
	v_and_b32_e32 v2, 60, v5
	v_lshlrev_b32_e32 v6, 7, v106
	v_lshlrev_b32_e32 v7, 2, v7
	v_bitop3_b32 v5, v108, 28, v5 bitop3:0x48
	s_cselect_b64 s[6:7], -1, 0
	s_cmp_lg_u64 s[44:45], 0
	v_readlane_b32 s36, v253, 2
	v_add3_u32 v107, v3, v6, v7
	v_lshlrev_b32_e32 v6, 7, v108
	v_lshlrev_b32_e32 v5, 2, v5
	v_readlane_b32 s40, v253, 6
	v_readlane_b32 s41, v253, 7
	v_lshlrev_b32_e32 v67, 1, v4
	v_add3_u32 v109, v3, v6, v5
	v_lshlrev_b32_e32 v3, 11, v4
	v_lshlrev_b32_e32 v4, 12, v4
	s_cselect_b64 s[8:9], -1, 0
	v_readlane_b32 s37, v253, 3
	v_readlane_b32 s38, v253, 4
	v_readlane_b32 s39, v253, 5
	s_cmp_lg_u64 s[40:41], 0
	v_lshlrev_b32_e32 v5, 2, v11
	v_readlane_b32 s0, v253, 34
	s_movk_i32 s16, 0xf000
	v_mov_b32_e32 v69, 0
	v_lshlrev_b32_e32 v86, 7, v2
	v_and_b32_e32 v70, 56, v12
	s_cselect_b64 s[12:13], -1, 0
	v_lshl_add_u32 v110, v11, 6, s24
	s_lshl_b32 s11, s10, 6
	v_lshl_add_u32 v111, s0, 5, v5
	s_lshl_b32 s36, s10, 2
	v_mov_b64_e32 v[72:73], s[92:93]
	s_movk_i32 s37, 0x2000
	s_mov_b32 s38, 0x10000
	s_mov_b32 s39, 0x12000
	s_mov_b32 s2, 0x20000
	s_mov_b32 s3, 0x22000
	s_mov_b32 s76, 0x30000
	s_mov_b32 s77, 0x32000
	s_mov_b32 s78, 0x40000
	s_mov_b32 s79, 0x42000
	s_mov_b32 s80, 0x50000
	s_mov_b32 s81, 0x52000
	s_mov_b32 s82, 0x60000
	s_mov_b32 s83, 0x62000
	s_mov_b32 s84, 0x70000
	v_lshlrev_b32_e32 v112, 2, v3
	s_mov_b32 s85, 0x39000
	v_lshlrev_b32_e32 v113, 2, v4
	s_mov_b32 s86, 0x48000
	s_mov_b32 s87, 0x80000
	s_mov_b32 s88, 0x88000
	s_mov_b32 s89, 0xc0000
	s_mov_b32 s56, 0xc8000
	s_mov_b32 s57, 0x100000
	s_mov_b32 s58, 0x108000
	s_mov_b32 s59, 0x140000
	s_mov_b32 s60, 0x148000
	s_mov_b32 s61, 0x180000
	s_mov_b32 s64, 0x1400000
	s_mov_b32 s65, 0x14000
	s_mov_b32 s66, 0x16000
	s_mov_b32 s67, 0x2a000
	s_mov_b32 s68, 0x3c000
	s_mov_b32 s69, 0x3e000
	v_lshlrev_b32_e32 v68, 2, v2
	v_mov_b32_e32 v114, 6
	s_mov_b32 s70, 0x64000
	s_mov_b32 s71, 0x66000
	s_mov_b32 s72, 0x78000
	s_movk_i32 s73, 0x4ff
	s_mov_b64 s[14:15], 0
	s_mov_b32 s17, -1
	s_mov_b64 s[18:19], 0xc00000
	s_mov_b64 s[20:21], 0xa00000
	s_mov_b64 s[22:23], 0x3400000
	s_mov_b64 s[24:25], 0x1400000
	v_readlane_b32 s42, v253, 8
	v_readlane_b32 s43, v253, 9
	v_readlane_b32 s44, v253, 10
	v_readlane_b32 s45, v253, 11
	v_readlane_b32 s46, v253, 12
	v_readlane_b32 s47, v253, 13
	v_readlane_b32 s48, v253, 14
	v_readlane_b32 s49, v253, 15
	v_readlane_b32 s50, v253, 16
	v_readlane_b32 s51, v253, 17
	s_branch .LBB0_118

; __device__ __forceinline__ void p0_prologue(const Params& p, LAS unsigned char* lds, int tid) {
;     ...
;     for (int it = gw; it < I_LAYER * DEPTH; it += NGW) {
;         const int l = it / I_LAYER; int r = it % I_LAYER;
;         unsigned char* wl = p.ws + (size_t)l * LAYER_BYTES;
;         if (r < I_IN) { p0_transpose_item(p.in[3] + (size_t)l * DM * INW, DM, INW, p.in[2] + l * DM, nullptr, (bf16_t*)(wl + LO_WIN), scr, r, lane); continue; } r -= I_IN;
;         if (r < I_UP) { p0_transpose_item(p.in[21] + (size_t)l * DM * DFF, DM, DFF, p.in[20] + l * DM, nullptr, (bf16_t*)(wl + LO_WUP), scr, r, lane); continue; } r -= I_UP;
;         if (r < I_DN) { p0_transpose_item(p.in[22] + (size_t)l * DFF * DM, DFF, DM, nullptr, nullptr, (bf16_t*)(wl + LO_WDN), scr, r, lane); continue; } r -= I_DN;
;         if (r < I_GLU) { p0_transpose_item(p.in[15] + (size_t)l * 1024 * 1024, 1024, 1024, nullptr, nullptr, (bf16_t*)(wl + LO_WGLU), scr, r, lane); continue; } r -= I_GLU;
;         p0_transpose_item(p.in[19] + (size_t)l * DM * DM, DM, DM, p.in[17] + l * 1024, p.in[18] + l * 1024, (bf16_t*)(wl + LO_WOUT), scr, r, lane);
;     }
.LBB0_427:
	v_readlane_b32 s98, v254, 36
	v_readlane_b32 s99, v253, 34
	s_cmp_lt_u32 s99, 64
	s_cbranch_scc1 .Lmy_w_skip
	v_writelane_b32 v140, s0, 0
	v_writelane_b32 v140, s1, 1
	v_writelane_b32 v140, s2, 2
	v_writelane_b32 v140, s3, 3
	v_writelane_b32 v140, s4, 4
	v_writelane_b32 v140, s5, 5
	v_writelane_b32 v140, s6, 6
	v_writelane_b32 v140, s7, 7
	v_writelane_b32 v140, s8, 8
	v_writelane_b32 v140, s9, 9
	v_writelane_b32 v140, s10, 10
	v_writelane_b32 v140, s11, 11
	v_writelane_b32 v140, s12, 12
	v_writelane_b32 v140, s13, 13
	v_writelane_b32 v140, s14, 14
	v_writelane_b32 v140, s15, 15
	v_writelane_b32 v140, s16, 16
	v_writelane_b32 v140, s17, 17
	v_writelane_b32 v140, s18, 18
	v_writelane_b32 v140, s19, 19
	v_writelane_b32 v140, s20, 20
	v_writelane_b32 v140, s21, 21
	v_writelane_b32 v140, s22, 22
	v_writelane_b32 v140, s23, 23
	v_writelane_b32 v140, s24, 24
	v_writelane_b32 v140, s25, 25
	v_writelane_b32 v140, s26, 26
	v_writelane_b32 v140, s27, 27
	v_writelane_b32 v140, s28, 28
	v_writelane_b32 v140, s29, 29
	v_writelane_b32 v140, s30, 30
	v_writelane_b32 v140, s31, 31
	v_writelane_b32 v140, s32, 32
	v_writelane_b32 v140, s33, 33
	v_writelane_b32 v140, s34, 34
	v_writelane_b32 v140, s35, 35
	v_writelane_b32 v140, s36, 36
	v_writelane_b32 v140, s37, 37
	v_writelane_b32 v140, s38, 38
	v_writelane_b32 v140, s39, 39
	v_writelane_b32 v140, s40, 40
	v_writelane_b32 v140, s41, 41
	v_writelane_b32 v140, s42, 42
	v_writelane_b32 v140, s43, 43
	v_writelane_b32 v140, s44, 44
	v_writelane_b32 v140, s45, 45
	v_writelane_b32 v140, s46, 46
	v_writelane_b32 v140, s47, 47
	v_writelane_b32 v140, s48, 48
	v_writelane_b32 v140, s49, 49
	v_writelane_b32 v140, s50, 50
	v_writelane_b32 v140, s51, 51
	v_writelane_b32 v140, s52, 52
	v_writelane_b32 v140, s53, 53
	v_writelane_b32 v140, s54, 54
	v_writelane_b32 v140, s55, 55
	v_writelane_b32 v140, s56, 56
	v_writelane_b32 v140, s57, 57
	v_writelane_b32 v140, s58, 58
	v_writelane_b32 v140, s59, 59
	v_writelane_b32 v140, s60, 60
	v_writelane_b32 v140, s61, 61
	v_writelane_b32 v140, s62, 62
	v_writelane_b32 v140, s63, 63
	v_writelane_b32 v141, s64, 0
	v_writelane_b32 v141, s65, 1
	v_writelane_b32 v141, s66, 2
	v_writelane_b32 v141, s67, 3
	v_writelane_b32 v141, s68, 4
	v_writelane_b32 v141, s69, 5
	v_writelane_b32 v141, s70, 6
	v_writelane_b32 v141, s71, 7
	v_writelane_b32 v141, s72, 8
	v_writelane_b32 v141, s73, 9
	v_writelane_b32 v141, s74, 10
	v_writelane_b32 v141, s75, 11
	v_writelane_b32 v141, s76, 12
	v_writelane_b32 v141, s77, 13
	v_writelane_b32 v141, s78, 14
	v_writelane_b32 v141, s79, 15
	v_writelane_b32 v141, s80, 16
	v_writelane_b32 v141, s81, 17
	v_writelane_b32 v141, s82, 18
	v_writelane_b32 v141, s83, 19
	v_writelane_b32 v141, s84, 20
	v_writelane_b32 v141, s85, 21
	v_writelane_b32 v141, s86, 22
	v_writelane_b32 v141, s87, 23
	v_writelane_b32 v141, s88, 24
	v_writelane_b32 v141, s89, 25
	v_writelane_b32 v141, s90, 26
	v_writelane_b32 v141, s91, 27
	v_writelane_b32 v141, s92, 28
	v_writelane_b32 v141, s93, 29
	v_writelane_b32 v141, s94, 30
	v_writelane_b32 v141, s95, 31
	v_writelane_b32 v141, s96, 32
	v_writelane_b32 v141, s97, 33
	s_mul_i32 s98, s98, 0x2a00
	s_add_i32 s0, s98, 0x500
	s_add_i32 s98, s0, 0x2a00
	s_min_u32 s98, s98, 0xa800
	s_sub_i32 s1, s99, 64
	s_lshl_b32 s1, s1, 3
	s_add_i32 s0, s0, s1
	v_and_b32_e32 v34, 63, v201
	v_lshrrev_b32_e32 v35, 6, v201
	v_lshlrev_b32_e32 v36, 3, v201
	v_add_u32_e32 v90, s0, v35
	s_add_i32 s99, s98, -1
	s_sub_i32 s10, s94, 64
	s_lshl_b32 s10, s10, 3
	v_readlane_b32 s62, v255, 8
	v_readlane_b32 s63, v255, 9
	s_branch .Lmy_w_entry
